# prompt ticket: second unit's query/weight loads requested before the first unit's selection (prologue de-serialisation across units)
# baseline (speedup 1.0000x reference)
; #define PG8_LAS __attribute__((address_space(3)))
; __device__ __forceinline__ unsigned fkey(float f) { const unsigned u = __float_as_uint(f); return (u & 0x80000000u) ? ~u : (u | 0x80000000u); }
; __device__ __forceinline__ void idx_load_q(IdxQ& q, const bf16_t* QI, const float* WI, int grow0, int lane) {
;     static_assert(IDX_SPLIT == 1, "q_idx is stored in bf16");
;     const int rho = lane & 31, kh = lane >> 5, ql = 2 * ((rho >> 2) & 1) + (rho >> 4), head = 4 * ((rho >> 3) & 1) + (rho & 3);
;     const bf16_t* src = QI + (size_t)(grow0 + ql) * 512 + head * IDD + kh * 8;
; #pragma unroll
;     for (int ks = 0; ks < 4; ++ks) { q.hi[ks] = *(const bf16x8*)(src + ks * 16); q.lo[ks] = q.hi[ks]; }
; #pragma unroll
;     for (int e = 0; e < 2; ++e) {
;         const float* wsrc = WI + (size_t)(grow0 + 2 * kh + e) * 8;
;         const f32x4 a = *(const f32x4*)wsrc, b = *(const f32x4*)(wsrc + 4);
; #pragma unroll
;         for (int i = 0; i < 4; ++i) { q.w[e * 8 + i] = a[i] * IDX_W_SCALE; q.w[e * 8 + 4 + i] = b[i] * IDX_W_SCALE; }
;     }
;     ...
;     const int nj = __builtin_amdgcn_readfirstlane((n + 63) >> 6), ng = (nj + 7) >> 3;
;     const PG8_LAS float* pl = sc + lane;
; #pragma unroll
;     for (int j = 0; j < NJ; ++j) { const unsigned k = fkey(pl[j * 64]); v[j] = (lane < n - j * 64) ? k : 0u; }
.LidxA_done:
.LBB0_879:
	v_lshrrev_b32_e32 v151, 5, v84
	v_lshrrev_b32_e32 v152, 1, v84
	v_and_b32_e32 v153, 2, v152
	v_bfe_u32 v154, v0, 4, 1
	v_and_b32_e32 v155, 3, v0
	v_and_or_b32 v155, v152, 4, v155
	v_or3_b32 v153, s10, v154, v153
	v_lshlrev_b32_e32 v153, 10, v153
	v_lshl_add_u32 v153, v155, 7, v153
	v_lshl_add_u32 v153, v151, 4, v153
	v_add_u32_e32 v154, 0x1000, v153
	s_lshl_b32 s1, s10, 5
	v_lshl_add_u32 v155, v151, 6, s1
	global_load_dwordx4 v[176:179], v153, s[64:65]
	global_load_dwordx4 v[180:183], v153, s[64:65] offset:32
	global_load_dwordx4 v[184:187], v153, s[64:65] offset:64
	global_load_dwordx4 v[188:191], v153, s[64:65] offset:96
	global_load_dwordx4 v[192:195], v154, s[64:65]
	global_load_dwordx4 v[196:199], v154, s[64:65] offset:32
	global_load_dwordx4 v[200:203], v154, s[64:65] offset:64
	global_load_dwordx4 v[204:207], v154, s[64:65] offset:96
	global_load_dwordx4 v[208:211], v155, s[66:67]
	global_load_dwordx4 v[212:215], v155, s[66:67] offset:16
	global_load_dwordx4 v[216:219], v155, s[66:67] offset:32
	global_load_dwordx4 v[220:223], v155, s[66:67] offset:48
	global_load_dwordx4 v[224:227], v155, s[66:67] offset:128
	global_load_dwordx4 v[228:231], v155, s[66:67] offset:144
	global_load_dwordx4 v[232:235], v155, s[66:67] offset:160
	global_load_dwordx4 v[240:243], v155, s[66:67] offset:176
	s_lshl_b32 s0, s4, 14
	s_add_i32 s1, s0, 0
	v_lshl_add_u32 v2, v84, 2, s1
	s_waitcnt lgkmcnt(0)
	s_barrier
	ds_read2st64_b32 v[4:5], v2 offset1:1
	s_add_i32 s0, s4, s10
	ds_read2st64_b32 v[8:9], v2 offset0:2 offset1:3
	ds_read2st64_b32 v[10:11], v2 offset0:4 offset1:5
	ds_read2st64_b32 v[12:13], v2 offset0:6 offset1:7
	s_add_i32 s3, s0, 64
	s_ashr_i32 s5, s3, 6
	s_waitcnt lgkmcnt(3)
	v_not_b32_e32 v3, v4
	v_or_b32_e32 v6, 0x80000000, v4
	v_cmp_gt_i32_e32 vcc, 0, v4
	s_sub_i32 s3, s0, 63
	s_waitcnt lgkmcnt(2)
	v_and_b32_e32 v15, 0x7fffffff, v8
	v_cndmask_b32_e32 v3, v6, v3, vcc
	v_cmp_ge_i32_e32 vcc, s0, v84
	v_or_b32_e32 v6, 0x80000000, v5
	v_and_b32_e32 v14, 0x7fffffff, v9
	v_cndmask_b32_e32 v4, 0, v3, vcc
	v_not_b32_e32 v3, v5
	v_cmp_gt_i32_e32 vcc, 0, v5
	v_xor_b32_e32 v5, -1, v9
	v_pk_add_f32 v[14:15], v[14:15], 0 neg_lo:[1,1] neg_hi:[1,1]
	v_cndmask_b32_e32 v3, v6, v3, vcc
	v_cmp_gt_i32_e32 vcc, s3, v84
	s_add_i32 s3, s0, 0xffffff81
	s_add_i32 s6, s0, 0xffffff41
	v_cndmask_b32_e32 v6, 0, v3, vcc
	v_cmp_gt_i32_e32 vcc, 0, v9
	v_xor_b32_e32 v3, -1, v8
	s_waitcnt lgkmcnt(1)
	v_xor_b32_e32 v7, -1, v11
	v_cndmask_b32_e32 v5, v14, v5, vcc
	v_cmp_gt_i32_e32 vcc, 0, v8
	v_and_b32_e32 v14, 0x7fffffff, v11
	s_add_i32 s1, s5, 7
	v_cndmask_b32_e32 v3, v15, v3, vcc
	v_cmp_gt_i32_e32 vcc, s3, v84
	v_and_b32_e32 v15, 0x7fffffff, v10
	v_pk_add_f32 v[14:15], v[14:15], 0 neg_lo:[1,1] neg_hi:[1,1]
	v_cndmask_b32_e32 v9, 0, v3, vcc
	v_cmp_gt_i32_e32 vcc, s6, v84
	v_xor_b32_e32 v3, -1, v10
	s_add_i32 s3, s0, 0xffffff01
	v_cndmask_b32_e32 v5, 0, v5, vcc
	v_cmp_gt_i32_e32 vcc, 0, v11
	s_add_i32 s6, s0, 0xfffffec1
	s_waitcnt lgkmcnt(0)
	v_and_b32_e32 v11, 0x7fffffff, v12
	v_cndmask_b32_e32 v7, v14, v7, vcc
	v_cmp_gt_i32_e32 vcc, 0, v10
	v_and_b32_e32 v10, 0x7fffffff, v13
	v_xor_b32_e32 v14, -1, v13
	v_cndmask_b32_e32 v3, v15, v3, vcc
	v_cmp_gt_i32_e32 vcc, s3, v84
	v_pk_add_f32 v[10:11], v[10:11], 0 neg_lo:[1,1] neg_hi:[1,1]
	s_add_i32 s3, s0, 0xfffffe81
	v_cndmask_b32_e32 v8, 0, v3, vcc
	v_cmp_gt_i32_e32 vcc, s6, v84
	s_add_i32 s6, s0, 0xfffffe41
	s_ashr_i32 s13, s1, 3
	v_cndmask_b32_e32 v3, 0, v7, vcc
	v_cmp_gt_i32_e32 vcc, 0, v13
	v_xor_b32_e32 v7, -1, v12
	s_nop 0
	v_cndmask_b32_e32 v14, v10, v14, vcc
	v_cmp_gt_i32_e32 vcc, 0, v12
	ds_read2st64_b32 v[12:13], v2 offset0:8 offset1:9
	s_waitcnt lgkmcnt(0)
	v_and_b32_e32 v17, 0x7fffffff, v12
	v_cndmask_b32_e32 v7, v11, v7, vcc
	v_cmp_gt_i32_e32 vcc, s3, v84
	v_and_b32_e32 v16, 0x7fffffff, v13
	v_xor_b32_e32 v22, -1, v13
	v_cndmask_b32_e32 v10, 0, v7, vcc
	v_cmp_gt_i32_e32 vcc, s6, v84
	v_pk_add_f32 v[16:17], v[16:17], 0 neg_lo:[1,1] neg_hi:[1,1]
	v_xor_b32_e32 v11, -1, v12
	v_cndmask_b32_e32 v7, 0, v14, vcc
	ds_read2st64_b32 v[14:15], v2 offset0:10 offset1:11
	ds_read2st64_b32 v[18:19], v2 offset0:12 offset1:13
	ds_read2st64_b32 v[20:21], v2 offset0:14 offset1:15
	v_cmp_gt_i32_e32 vcc, 0, v13
	s_add_i32 s3, s0, 0xfffffe01
	s_add_i32 s6, s0, 0xfffffdc1
	v_cndmask_b32_e32 v13, v16, v22, vcc
	v_cmp_gt_i32_e32 vcc, 0, v12
	s_waitcnt lgkmcnt(2)
	v_and_b32_e32 v23, 0x7fffffff, v14
	v_and_b32_e32 v22, 0x7fffffff, v15
	v_cndmask_b32_e32 v11, v17, v11, vcc
	v_cmp_gt_i32_e32 vcc, s3, v84
	v_xor_b32_e32 v12, -1, v15
	v_pk_add_f32 v[22:23], v[22:23], 0 neg_lo:[1,1] neg_hi:[1,1]
	v_cndmask_b32_e32 v17, 0, v11, vcc
	v_cmp_gt_i32_e32 vcc, s6, v84
	v_xor_b32_e32 v11, -1, v14
	s_add_i32 s3, s0, 0xfffffd81
	v_cndmask_b32_e32 v13, 0, v13, vcc
	v_cmp_gt_i32_e32 vcc, 0, v15
	s_add_i32 s6, s0, 0xfffffd41
	s_waitcnt lgkmcnt(1)
	v_and_b32_e32 v15, 0x7fffffff, v18
	v_cndmask_b32_e32 v12, v22, v12, vcc
	v_cmp_gt_i32_e32 vcc, 0, v14
	v_and_b32_e32 v14, 0x7fffffff, v19
	v_xor_b32_e32 v22, -1, v19
	v_cndmask_b32_e32 v11, v23, v11, vcc
	v_cmp_gt_i32_e32 vcc, s3, v84
	v_pk_add_f32 v[14:15], v[14:15], 0 neg_lo:[1,1] neg_hi:[1,1]
	s_add_i32 s3, s0, 0xfffffd01
	v_cndmask_b32_e32 v16, 0, v11, vcc
	v_cmp_gt_i32_e32 vcc, s6, v84
	v_xor_b32_e32 v11, -1, v18
	s_add_i32 s6, s0, 0xfffffcc1
	v_cndmask_b32_e32 v12, 0, v12, vcc
	v_cmp_gt_i32_e32 vcc, 0, v19
	s_waitcnt lgkmcnt(0)
; #define PG8_LAS __attribute__((address_space(3)))
; __device__ __forceinline__ unsigned fkey(float f) { const unsigned u = __float_as_uint(f); return (u & 0x80000000u) ? ~u : (u | 0x80000000u); }
;     ...
;     const int nj = __builtin_amdgcn_readfirstlane((n + 63) >> 6), ng = (nj + 7) >> 3;
;     const PG8_LAS float* pl = sc + lane;
; #pragma unroll
;     for (int j = 0; j < NJ; ++j) { const unsigned k = fkey(pl[j * 64]); v[j] = (lane < n - j * 64) ? k : 0u; }
	v_and_b32_e32 v19, 0x7fffffff, v20
	v_cndmask_b32_e32 v14, v14, v22, vcc
	v_cmp_gt_i32_e32 vcc, 0, v18
	v_and_b32_e32 v18, 0x7fffffff, v21
	v_xor_b32_e32 v22, -1, v21
	v_cndmask_b32_e32 v11, v15, v11, vcc
	v_cmp_gt_i32_e32 vcc, s3, v84
	v_pk_add_f32 v[18:19], v[18:19], 0 neg_lo:[1,1] neg_hi:[1,1]
	s_add_i32 s3, s0, 0xfffffc81
	v_cndmask_b32_e32 v15, 0, v11, vcc
	v_cmp_gt_i32_e32 vcc, s6, v84
	s_add_i32 s6, s0, 0xfffffc41
	s_nop 0
	v_cndmask_b32_e32 v11, 0, v14, vcc
	v_cmp_gt_i32_e32 vcc, 0, v21
	v_xor_b32_e32 v14, -1, v20
	s_nop 0
	v_cndmask_b32_e32 v22, v18, v22, vcc
	v_cmp_gt_i32_e32 vcc, 0, v20
	ds_read2st64_b32 v[20:21], v2 offset0:16 offset1:17
	s_waitcnt lgkmcnt(0)
	v_and_b32_e32 v25, 0x7fffffff, v20
	v_cndmask_b32_e32 v14, v19, v14, vcc
	v_cmp_gt_i32_e32 vcc, s3, v84
	v_and_b32_e32 v24, 0x7fffffff, v21
	v_xor_b32_e32 v30, -1, v21
	v_cndmask_b32_e32 v18, 0, v14, vcc
	v_cmp_gt_i32_e32 vcc, s6, v84
	v_pk_add_f32 v[24:25], v[24:25], 0 neg_lo:[1,1] neg_hi:[1,1]
	v_xor_b32_e32 v19, -1, v20
	v_cndmask_b32_e32 v14, 0, v22, vcc
	ds_read2st64_b32 v[22:23], v2 offset0:18 offset1:19
	ds_read2st64_b32 v[26:27], v2 offset0:20 offset1:21
	ds_read2st64_b32 v[28:29], v2 offset0:22 offset1:23
	v_cmp_gt_i32_e32 vcc, 0, v21
	s_add_i32 s3, s0, 0xfffffc01
	s_add_i32 s6, s0, 0xfffffbc1
	v_cndmask_b32_e32 v21, v24, v30, vcc
	v_cmp_gt_i32_e32 vcc, 0, v20
	s_waitcnt lgkmcnt(2)
	v_and_b32_e32 v31, 0x7fffffff, v22
	v_and_b32_e32 v30, 0x7fffffff, v23
	v_cndmask_b32_e32 v19, v25, v19, vcc
	v_cmp_gt_i32_e32 vcc, s3, v84
	v_xor_b32_e32 v20, -1, v23
	v_pk_add_f32 v[30:31], v[30:31], 0 neg_lo:[1,1] neg_hi:[1,1]
	v_cndmask_b32_e32 v25, 0, v19, vcc
	v_cmp_gt_i32_e32 vcc, s6, v84
	v_xor_b32_e32 v19, -1, v22
	s_add_i32 s3, s0, 0xfffffb81
	v_cndmask_b32_e32 v21, 0, v21, vcc
	v_cmp_gt_i32_e32 vcc, 0, v23
	s_add_i32 s6, s0, 0xfffffb41
	s_waitcnt lgkmcnt(1)
	v_and_b32_e32 v23, 0x7fffffff, v26
	v_cndmask_b32_e32 v20, v30, v20, vcc
	v_cmp_gt_i32_e32 vcc, 0, v22
	v_and_b32_e32 v22, 0x7fffffff, v27
	v_xor_b32_e32 v30, -1, v27
	v_cndmask_b32_e32 v19, v31, v19, vcc
	v_cmp_gt_i32_e32 vcc, s3, v84
	v_pk_add_f32 v[22:23], v[22:23], 0 neg_lo:[1,1] neg_hi:[1,1]
	s_add_i32 s3, s0, 0xfffffb01
	v_cndmask_b32_e32 v24, 0, v19, vcc
	v_cmp_gt_i32_e32 vcc, s6, v84
	v_xor_b32_e32 v19, -1, v26
	s_add_i32 s6, s0, 0xfffffac1
	v_cndmask_b32_e32 v20, 0, v20, vcc
	v_cmp_gt_i32_e32 vcc, 0, v27
	s_waitcnt lgkmcnt(0)
	v_and_b32_e32 v27, 0x7fffffff, v28
	v_cndmask_b32_e32 v22, v22, v30, vcc
	v_cmp_gt_i32_e32 vcc, 0, v26
	v_and_b32_e32 v26, 0x7fffffff, v29
	v_xor_b32_e32 v30, -1, v29
	v_cndmask_b32_e32 v19, v23, v19, vcc
	v_cmp_gt_i32_e32 vcc, s3, v84
	v_pk_add_f32 v[26:27], v[26:27], 0 neg_lo:[1,1] neg_hi:[1,1]
	s_add_i32 s3, s0, 0xfffffa81
	v_cndmask_b32_e32 v23, 0, v19, vcc
	v_cmp_gt_i32_e32 vcc, s6, v84
	s_add_i32 s6, s0, 0xfffffa41
	s_nop 0
	v_cndmask_b32_e32 v19, 0, v22, vcc
	v_cmp_gt_i32_e32 vcc, 0, v29
	v_xor_b32_e32 v22, -1, v28
	s_nop 0
	v_cndmask_b32_e32 v30, v26, v30, vcc
	v_cmp_gt_i32_e32 vcc, 0, v28
	ds_read2st64_b32 v[28:29], v2 offset0:24 offset1:25
	s_waitcnt lgkmcnt(0)
	v_and_b32_e32 v33, 0x7fffffff, v28
	v_cndmask_b32_e32 v22, v27, v22, vcc
	v_cmp_gt_i32_e32 vcc, s3, v84
	v_and_b32_e32 v32, 0x7fffffff, v29
	v_xor_b32_e32 v38, -1, v29
	v_cndmask_b32_e32 v26, 0, v22, vcc
	v_cmp_gt_i32_e32 vcc, s6, v84
	v_pk_add_f32 v[32:33], v[32:33], 0 neg_lo:[1,1] neg_hi:[1,1]
	v_xor_b32_e32 v27, -1, v28
	v_cndmask_b32_e32 v22, 0, v30, vcc
	ds_read2st64_b32 v[30:31], v2 offset0:26 offset1:27
	ds_read2st64_b32 v[34:35], v2 offset0:28 offset1:29
	ds_read2st64_b32 v[36:37], v2 offset0:30 offset1:31
	v_cmp_gt_i32_e32 vcc, 0, v29
	s_add_i32 s3, s0, 0xfffffa01
	s_add_i32 s6, s0, 0xfffff9c1
	v_cndmask_b32_e32 v29, v32, v38, vcc
	v_cmp_gt_i32_e32 vcc, 0, v28
	s_waitcnt lgkmcnt(2)
	v_and_b32_e32 v39, 0x7fffffff, v30
	v_and_b32_e32 v38, 0x7fffffff, v31
	v_cndmask_b32_e32 v27, v33, v27, vcc
	v_cmp_gt_i32_e32 vcc, s3, v84
	v_xor_b32_e32 v28, -1, v31
	v_pk_add_f32 v[38:39], v[38:39], 0 neg_lo:[1,1] neg_hi:[1,1]
	v_cndmask_b32_e32 v33, 0, v27, vcc
	v_cmp_gt_i32_e32 vcc, s6, v84
	v_xor_b32_e32 v27, -1, v30
	s_add_i32 s3, s0, 0xfffff981
	v_cndmask_b32_e32 v29, 0, v29, vcc
	v_cmp_gt_i32_e32 vcc, 0, v31
	s_add_i32 s6, s0, 0xfffff941
	s_waitcnt lgkmcnt(1)
	v_and_b32_e32 v31, 0x7fffffff, v34
	v_cndmask_b32_e32 v28, v38, v28, vcc
	v_cmp_gt_i32_e32 vcc, 0, v30
	v_and_b32_e32 v30, 0x7fffffff, v35
	v_xor_b32_e32 v38, -1, v35
	v_cndmask_b32_e32 v27, v39, v27, vcc
	v_cmp_gt_i32_e32 vcc, s3, v84
	v_pk_add_f32 v[30:31], v[30:31], 0 neg_lo:[1,1] neg_hi:[1,1]
	s_add_i32 s3, s0, 0xfffff901
	v_cndmask_b32_e32 v32, 0, v27, vcc
	v_cmp_gt_i32_e32 vcc, s6, v84
	v_xor_b32_e32 v27, -1, v34
	s_add_i32 s6, s0, 0xfffff8c1
	v_cndmask_b32_e32 v28, 0, v28, vcc
	v_cmp_gt_i32_e32 vcc, 0, v35
	s_waitcnt lgkmcnt(0)
	v_and_b32_e32 v35, 0x7fffffff, v36
	v_cndmask_b32_e32 v30, v30, v38, vcc
	v_cmp_gt_i32_e32 vcc, 0, v34
	v_and_b32_e32 v34, 0x7fffffff, v37
	v_xor_b32_e32 v38, -1, v37
	v_cndmask_b32_e32 v27, v31, v27, vcc
	v_cmp_gt_i32_e32 vcc, s3, v84
	v_pk_add_f32 v[34:35], v[34:35], 0 neg_lo:[1,1] neg_hi:[1,1]
	s_add_i32 s3, s0, 0xfffff881
	v_cndmask_b32_e32 v31, 0, v27, vcc
	v_cmp_gt_i32_e32 vcc, s6, v84
	s_add_i32 s6, s0, 0xfffff841
	s_nop 0
	v_cndmask_b32_e32 v27, 0, v30, vcc
	v_cmp_gt_i32_e32 vcc, 0, v37
	v_xor_b32_e32 v30, -1, v36
	s_nop 0
	v_cndmask_b32_e32 v38, v34, v38, vcc
	v_cmp_gt_i32_e32 vcc, 0, v36
	ds_read2st64_b32 v[36:37], v2 offset0:32 offset1:33
	s_waitcnt lgkmcnt(0)
; #define PG8_LAS __attribute__((address_space(3)))
; __device__ __forceinline__ unsigned fkey(float f) { const unsigned u = __float_as_uint(f); return (u & 0x80000000u) ? ~u : (u | 0x80000000u); }
;     ...
;     const int nj = __builtin_amdgcn_readfirstlane((n + 63) >> 6), ng = (nj + 7) >> 3;
;     const PG8_LAS float* pl = sc + lane;
; #pragma unroll
;     for (int j = 0; j < NJ; ++j) { const unsigned k = fkey(pl[j * 64]); v[j] = (lane < n - j * 64) ? k : 0u; }
	v_and_b32_e32 v41, 0x7fffffff, v36
	v_cndmask_b32_e32 v30, v35, v30, vcc
	v_cmp_gt_i32_e32 vcc, s3, v84
	v_and_b32_e32 v40, 0x7fffffff, v37
	v_xor_b32_e32 v46, -1, v37
	v_cndmask_b32_e32 v34, 0, v30, vcc
	v_cmp_gt_i32_e32 vcc, s6, v84
	v_pk_add_f32 v[40:41], v[40:41], 0 neg_lo:[1,1] neg_hi:[1,1]
	v_xor_b32_e32 v35, -1, v36
	v_cndmask_b32_e32 v30, 0, v38, vcc
	ds_read2st64_b32 v[38:39], v2 offset0:34 offset1:35
	ds_read2st64_b32 v[42:43], v2 offset0:36 offset1:37
	ds_read2st64_b32 v[44:45], v2 offset0:38 offset1:39
	v_cmp_gt_i32_e32 vcc, 0, v37
	s_add_i32 s3, s0, 0xfffff801
	s_add_i32 s6, s0, 0xfffff7c1
	v_cndmask_b32_e32 v37, v40, v46, vcc
	v_cmp_gt_i32_e32 vcc, 0, v36
	s_waitcnt lgkmcnt(2)
	v_and_b32_e32 v47, 0x7fffffff, v38
	v_and_b32_e32 v46, 0x7fffffff, v39
	v_cndmask_b32_e32 v35, v41, v35, vcc
	v_cmp_gt_i32_e32 vcc, s3, v84
	v_xor_b32_e32 v36, -1, v39
	v_pk_add_f32 v[46:47], v[46:47], 0 neg_lo:[1,1] neg_hi:[1,1]
	v_cndmask_b32_e32 v41, 0, v35, vcc
	v_cmp_gt_i32_e32 vcc, s6, v84
	v_xor_b32_e32 v35, -1, v38
	s_add_i32 s3, s0, 0xfffff781
	v_cndmask_b32_e32 v37, 0, v37, vcc
	v_cmp_gt_i32_e32 vcc, 0, v39
	s_add_i32 s6, s0, 0xfffff741
	s_waitcnt lgkmcnt(1)
	v_and_b32_e32 v39, 0x7fffffff, v42
	v_cndmask_b32_e32 v36, v46, v36, vcc
	v_cmp_gt_i32_e32 vcc, 0, v38
	v_and_b32_e32 v38, 0x7fffffff, v43
	v_xor_b32_e32 v46, -1, v43
	v_cndmask_b32_e32 v35, v47, v35, vcc
	v_cmp_gt_i32_e32 vcc, s3, v84
	v_pk_add_f32 v[38:39], v[38:39], 0 neg_lo:[1,1] neg_hi:[1,1]
	s_add_i32 s3, s0, 0xfffff701
	v_cndmask_b32_e32 v40, 0, v35, vcc
	v_cmp_gt_i32_e32 vcc, s6, v84
	v_xor_b32_e32 v35, -1, v42
	s_add_i32 s6, s0, 0xfffff6c1
	v_cndmask_b32_e32 v36, 0, v36, vcc
	v_cmp_gt_i32_e32 vcc, 0, v43
	s_waitcnt lgkmcnt(0)
	v_and_b32_e32 v43, 0x7fffffff, v44
	v_cndmask_b32_e32 v38, v38, v46, vcc
	v_cmp_gt_i32_e32 vcc, 0, v42
	v_and_b32_e32 v42, 0x7fffffff, v45
	v_xor_b32_e32 v46, -1, v45
	v_cndmask_b32_e32 v35, v39, v35, vcc
	v_cmp_gt_i32_e32 vcc, s3, v84
	v_pk_add_f32 v[42:43], v[42:43], 0 neg_lo:[1,1] neg_hi:[1,1]
	s_add_i32 s3, s0, 0xfffff681
	v_cndmask_b32_e32 v39, 0, v35, vcc
	v_cmp_gt_i32_e32 vcc, s6, v84
	s_add_i32 s6, s0, 0xfffff641
	s_nop 0
	v_cndmask_b32_e32 v35, 0, v38, vcc
	v_cmp_gt_i32_e32 vcc, 0, v45
	v_xor_b32_e32 v38, -1, v44
	s_nop 0
	v_cndmask_b32_e32 v46, v42, v46, vcc
	v_cmp_gt_i32_e32 vcc, 0, v44
	ds_read2st64_b32 v[44:45], v2 offset0:40 offset1:41
	s_waitcnt lgkmcnt(0)
	v_and_b32_e32 v49, 0x7fffffff, v44
	v_cndmask_b32_e32 v38, v43, v38, vcc
	v_cmp_gt_i32_e32 vcc, s3, v84
	v_and_b32_e32 v48, 0x7fffffff, v45
	v_xor_b32_e32 v54, -1, v45
	v_cndmask_b32_e32 v42, 0, v38, vcc
	v_cmp_gt_i32_e32 vcc, s6, v84
	v_pk_add_f32 v[48:49], v[48:49], 0 neg_lo:[1,1] neg_hi:[1,1]
	v_xor_b32_e32 v43, -1, v44
	v_cndmask_b32_e32 v38, 0, v46, vcc
	ds_read2st64_b32 v[46:47], v2 offset0:42 offset1:43
	ds_read2st64_b32 v[50:51], v2 offset0:44 offset1:45
	ds_read2st64_b32 v[52:53], v2 offset0:46 offset1:47
	v_cmp_gt_i32_e32 vcc, 0, v45
	s_add_i32 s3, s0, 0xfffff601
	s_add_i32 s6, s0, 0xfffff5c1
	v_cndmask_b32_e32 v45, v48, v54, vcc
	v_cmp_gt_i32_e32 vcc, 0, v44
	s_waitcnt lgkmcnt(2)
	v_and_b32_e32 v55, 0x7fffffff, v46
	v_and_b32_e32 v54, 0x7fffffff, v47
	v_cndmask_b32_e32 v43, v49, v43, vcc
	v_cmp_gt_i32_e32 vcc, s3, v84
	v_xor_b32_e32 v44, -1, v47
	v_pk_add_f32 v[54:55], v[54:55], 0 neg_lo:[1,1] neg_hi:[1,1]
	v_cndmask_b32_e32 v49, 0, v43, vcc
	v_cmp_gt_i32_e32 vcc, s6, v84
	v_xor_b32_e32 v43, -1, v46
	s_add_i32 s3, s0, 0xfffff581
	v_cndmask_b32_e32 v45, 0, v45, vcc
	v_cmp_gt_i32_e32 vcc, 0, v47
	s_add_i32 s6, s0, 0xfffff541
	s_waitcnt lgkmcnt(1)
	v_and_b32_e32 v47, 0x7fffffff, v50
	v_cndmask_b32_e32 v44, v54, v44, vcc
	v_cmp_gt_i32_e32 vcc, 0, v46
	v_and_b32_e32 v46, 0x7fffffff, v51
	v_xor_b32_e32 v54, -1, v51
	v_cndmask_b32_e32 v43, v55, v43, vcc
	v_cmp_gt_i32_e32 vcc, s3, v84
	v_pk_add_f32 v[46:47], v[46:47], 0 neg_lo:[1,1] neg_hi:[1,1]
	s_add_i32 s3, s0, 0xfffff501
	v_cndmask_b32_e32 v48, 0, v43, vcc
	v_cmp_gt_i32_e32 vcc, s6, v84
	v_xor_b32_e32 v43, -1, v50
	s_add_i32 s6, s0, 0xfffff4c1
	v_cndmask_b32_e32 v44, 0, v44, vcc
	v_cmp_gt_i32_e32 vcc, 0, v51
	s_waitcnt lgkmcnt(0)
	v_and_b32_e32 v51, 0x7fffffff, v52
	v_cndmask_b32_e32 v46, v46, v54, vcc
	v_cmp_gt_i32_e32 vcc, 0, v50
	v_and_b32_e32 v50, 0x7fffffff, v53
	v_xor_b32_e32 v54, -1, v53
	v_cndmask_b32_e32 v43, v47, v43, vcc
	v_cmp_gt_i32_e32 vcc, s3, v84
	v_pk_add_f32 v[50:51], v[50:51], 0 neg_lo:[1,1] neg_hi:[1,1]
	s_add_i32 s3, s0, 0xfffff481
	v_cndmask_b32_e32 v47, 0, v43, vcc
	v_cmp_gt_i32_e32 vcc, s6, v84
	s_add_i32 s6, s0, 0xfffff441
	s_nop 0
	v_cndmask_b32_e32 v43, 0, v46, vcc
	v_cmp_gt_i32_e32 vcc, 0, v53
	v_xor_b32_e32 v46, -1, v52
	s_nop 0
	v_cndmask_b32_e32 v54, v50, v54, vcc
	v_cmp_gt_i32_e32 vcc, 0, v52
	ds_read2st64_b32 v[52:53], v2 offset0:48 offset1:49
	s_waitcnt lgkmcnt(0)
; __device__ __forceinline__ unsigned fkey(float f) { const unsigned u = __float_as_uint(f); return (u & 0x80000000u) ? ~u : (u | 0x80000000u); }
;     ...
;     for (int j = 0; j < NJ; ++j) { const unsigned k = fkey(pl[j * 64]); v[j] = (lane < n - j * 64) ? k : 0u; }
;     unsigned T = 1u; int need = 1 << 30;
;     if (n > TOPK) {
;         unsigned prefix = 0u; bool exact;
;         if (NG >= 8 && ng > 7) exact = bit_search<(NG >= 8 ? 8 : NG), NJ, BITLO>(v, prefix);
;         else if (NG >= 7 && ng > 6) exact = bit_search<(NG >= 7 ? 7 : NG), NJ, BITLO>(v, prefix);
;         else if (NG >= 6 && ng > 5) exact = bit_search<(NG >= 6 ? 6 : NG), NJ, BITLO>(v, prefix);
;         else if (NG >= 5 && ng > 4) exact = bit_search<(NG >= 5 ? 5 : NG), NJ, BITLO>(v, prefix);
;         else if (NG >= 4 && ng > 3) exact = bit_search<(NG >= 4 ? 4 : NG), NJ, BITLO>(v, prefix);
;         else if (NG >= 3 && ng > 2) exact = bit_search<(NG >= 3 ? 3 : NG), NJ, BITLO>(v, prefix);
;         else if (NG >= 2 && ng > 1) exact = bit_search<(NG >= 2 ? 2 : NG), NJ, BITLO>(v, prefix);
;         else exact = bit_search<1, NJ, BITLO>(v, prefix);
	v_and_b32_e32 v57, 0x7fffffff, v52
	v_cndmask_b32_e32 v46, v51, v46, vcc
	v_cmp_gt_i32_e32 vcc, s3, v84
	v_and_b32_e32 v56, 0x7fffffff, v53
	v_xor_b32_e32 v62, -1, v53
	v_cndmask_b32_e32 v50, 0, v46, vcc
	v_cmp_gt_i32_e32 vcc, s6, v84
	v_pk_add_f32 v[56:57], v[56:57], 0 neg_lo:[1,1] neg_hi:[1,1]
	v_xor_b32_e32 v51, -1, v52
	v_cndmask_b32_e32 v46, 0, v54, vcc
	ds_read2st64_b32 v[54:55], v2 offset0:50 offset1:51
	ds_read2st64_b32 v[58:59], v2 offset0:52 offset1:53
	ds_read2st64_b32 v[60:61], v2 offset0:54 offset1:55
	v_cmp_gt_i32_e32 vcc, 0, v53
	s_add_i32 s3, s0, 0xfffff401
	s_add_i32 s6, s0, 0xfffff3c1
	v_cndmask_b32_e32 v53, v56, v62, vcc
	v_cmp_gt_i32_e32 vcc, 0, v52
	s_waitcnt lgkmcnt(2)
	v_and_b32_e32 v63, 0x7fffffff, v54
	v_and_b32_e32 v62, 0x7fffffff, v55
	v_cndmask_b32_e32 v51, v57, v51, vcc
	v_cmp_gt_i32_e32 vcc, s3, v84
	v_xor_b32_e32 v52, -1, v55
	v_pk_add_f32 v[62:63], v[62:63], 0 neg_lo:[1,1] neg_hi:[1,1]
	v_cndmask_b32_e32 v57, 0, v51, vcc
	v_cmp_gt_i32_e32 vcc, s6, v84
	v_xor_b32_e32 v51, -1, v54
	s_add_i32 s3, s0, 0xfffff381
	v_cndmask_b32_e32 v53, 0, v53, vcc
	v_cmp_gt_i32_e32 vcc, 0, v55
	s_add_i32 s6, s0, 0xfffff341
	s_waitcnt lgkmcnt(1)
	v_and_b32_e32 v55, 0x7fffffff, v58
	v_cndmask_b32_e32 v52, v62, v52, vcc
	v_cmp_gt_i32_e32 vcc, 0, v54
	v_and_b32_e32 v54, 0x7fffffff, v59
	v_xor_b32_e32 v62, -1, v59
	v_cndmask_b32_e32 v51, v63, v51, vcc
	v_cmp_gt_i32_e32 vcc, s3, v84
	v_pk_add_f32 v[54:55], v[54:55], 0 neg_lo:[1,1] neg_hi:[1,1]
	s_add_i32 s3, s0, 0xfffff301
	v_cndmask_b32_e32 v56, 0, v51, vcc
	v_cmp_gt_i32_e32 vcc, s6, v84
	v_xor_b32_e32 v51, -1, v58
	s_add_i32 s6, s0, 0xfffff2c1
	v_cndmask_b32_e32 v52, 0, v52, vcc
	v_cmp_gt_i32_e32 vcc, 0, v59
	s_waitcnt lgkmcnt(0)
	v_and_b32_e32 v59, 0x7fffffff, v60
	v_cndmask_b32_e32 v54, v54, v62, vcc
	v_cmp_gt_i32_e32 vcc, 0, v58
	v_and_b32_e32 v58, 0x7fffffff, v61
	v_xor_b32_e32 v62, -1, v61
	v_cndmask_b32_e32 v51, v55, v51, vcc
	v_cmp_gt_i32_e32 vcc, s3, v84
	v_pk_add_f32 v[58:59], v[58:59], 0 neg_lo:[1,1] neg_hi:[1,1]
	s_add_i32 s3, s0, 0xfffff281
	v_cndmask_b32_e32 v55, 0, v51, vcc
	v_cmp_gt_i32_e32 vcc, s6, v84
	s_add_i32 s6, s0, 0xfffff241
	s_nop 0
	v_cndmask_b32_e32 v51, 0, v54, vcc
	v_cmp_gt_i32_e32 vcc, 0, v61
	v_xor_b32_e32 v54, -1, v60
	s_nop 0
	v_cndmask_b32_e32 v62, v58, v62, vcc
	v_cmp_gt_i32_e32 vcc, 0, v60
	ds_read2st64_b32 v[60:61], v2 offset0:56 offset1:57
	s_waitcnt lgkmcnt(0)
	v_and_b32_e32 v65, 0x7fffffff, v60
	v_cndmask_b32_e32 v54, v59, v54, vcc
	v_cmp_gt_i32_e32 vcc, s3, v84
	v_and_b32_e32 v64, 0x7fffffff, v61
	v_xor_b32_e32 v59, -1, v61
	v_cndmask_b32_e32 v58, 0, v54, vcc
	v_cmp_gt_i32_e32 vcc, s6, v84
	v_pk_add_f32 v[64:65], v[64:65], 0 neg_lo:[1,1] neg_hi:[1,1]
	s_add_i32 s3, s0, 0xfffff201
	v_cndmask_b32_e32 v54, 0, v62, vcc
	ds_read2st64_b32 v[62:63], v2 offset0:58 offset1:59
	ds_read2st64_b32 v[66:67], v2 offset0:60 offset1:61
	ds_read2st64_b32 v[68:69], v2 offset0:62 offset1:63
	v_cmp_gt_i32_e32 vcc, 0, v61
	v_xor_b32_e32 v2, -1, v60
	s_add_i32 s6, s0, 0xfffff1c1
	v_cndmask_b32_e32 v59, v64, v59, vcc
	v_cmp_gt_i32_e32 vcc, 0, v60
	s_waitcnt lgkmcnt(2)
	v_and_b32_e32 v71, 0x7fffffff, v62
	v_and_b32_e32 v70, 0x7fffffff, v63
	v_cndmask_b32_e32 v2, v65, v2, vcc
	v_cmp_gt_i32_e32 vcc, s3, v84
	v_pk_add_f32 v[70:71], v[70:71], 0 neg_lo:[1,1] neg_hi:[1,1]
	s_add_i32 s3, s0, 0xfffff181
	v_cndmask_b32_e32 v65, 0, v2, vcc
	v_cmp_gt_i32_e32 vcc, s6, v84
	v_xor_b32_e32 v2, -1, v62
	s_add_i32 s6, s0, 0xfffff141
	v_cndmask_b32_e32 v61, 0, v59, vcc
	v_xor_b32_e32 v59, -1, v63
	v_cmp_gt_i32_e32 vcc, 0, v63
	s_waitcnt lgkmcnt(1)
	v_and_b32_e32 v63, 0x7fffffff, v66
	v_cndmask_b32_e32 v59, v70, v59, vcc
	v_cmp_gt_i32_e32 vcc, 0, v62
	v_and_b32_e32 v62, 0x7fffffff, v67
	v_pk_add_f32 v[62:63], v[62:63], 0 neg_lo:[1,1] neg_hi:[1,1]
	v_cndmask_b32_e32 v2, v71, v2, vcc
	v_cmp_gt_i32_e32 vcc, s3, v84
	s_add_i32 s3, s0, 0xfffff101
	s_nop 0
	v_cndmask_b32_e32 v64, 0, v2, vcc
	v_cmp_gt_i32_e32 vcc, s6, v84
	v_xor_b32_e32 v2, -1, v66
	s_add_i32 s6, s0, 0xfffff0c1
	v_cndmask_b32_e32 v60, 0, v59, vcc
	v_xor_b32_e32 v59, -1, v67
	v_cmp_gt_i32_e32 vcc, 0, v67
	s_waitcnt lgkmcnt(0)
	v_and_b32_e32 v67, 0x7fffffff, v68
	v_cndmask_b32_e32 v59, v62, v59, vcc
	v_cmp_gt_i32_e32 vcc, 0, v66
	v_and_b32_e32 v66, 0x7fffffff, v69
	v_pk_add_f32 v[66:67], v[66:67], 0 neg_lo:[1,1] neg_hi:[1,1]
	v_cndmask_b32_e32 v2, v63, v2, vcc
	v_cmp_gt_i32_e32 vcc, s3, v84
	v_xor_b32_e32 v63, -1, v69
	s_add_i32 s3, s0, 0xfffff081
	v_cndmask_b32_e32 v62, 0, v2, vcc
	v_cmp_gt_i32_e32 vcc, s6, v84
	v_xor_b32_e32 v2, -1, v68
	s_add_i32 s6, s0, 0xfffff041
	v_cndmask_b32_e32 v59, 0, v59, vcc
	v_cmp_gt_i32_e32 vcc, 0, v69
	s_cmpk_lt_i32 s0, 0x100
	s_nop 0
	v_cndmask_b32_e32 v63, v66, v63, vcc
	v_cmp_gt_i32_e32 vcc, 0, v68
	s_nop 1
	v_cndmask_b32_e32 v2, v67, v2, vcc
	v_cmp_gt_i32_e32 vcc, s3, v84
	s_nop 1
	v_cndmask_b32_e32 v66, 0, v2, vcc
	v_cmp_gt_i32_e32 vcc, s6, v84
	s_nop 1
	v_cndmask_b32_e32 v63, 0, v63, vcc
	s_cbranch_scc1 .LBB0_890
	s_cmp_gt_i32 s13, 7
	s_cselect_b64 s[0:1], -1, 0
	s_cmp_lt_i32 s13, 8
	s_cbranch_scc0 .LBB0_891
	s_cmp_lg_u32 s13, 7
	s_cbranch_scc0 .LBB0_892
	s_cmp_lt_i32 s13, 6
	s_cbranch_scc0 .LBB0_893
	s_cmp_lg_u32 s13, 5
	s_cbranch_scc0 .LBB0_894
	s_cmp_lt_i32 s13, 4
	s_cbranch_scc0 .LBB0_895
	s_cmp_lg_u32 s13, 3
	s_cbranch_scc0 .LBB0_896
	s_cmp_gt_i32 s13, 1
	s_cbranch_scc1 .LBB0_897
	v_mov_b32_e32 v2, 31
	v_mov_b32_e32 v67, 0

;     ...
;     const unsigned long long mymask = ((unsigned long long)mhi << 32) | mlo;
;     bm_row[lane] = mymask;
;     ...
;     IdxQ qa, qb; idx_load_q(qa, QI, WI, grow0, lane); idx_load_q(qb, QI, WI, grow0 + 4, lane);
;     const size_t kbase = (size_t)(b * SEQ + r) * IDD + kh * 8;
;     IdxKey kn;
;     if (wave < ntile) idx_load_keyb(kn, KIH + kbase + (size_t)wave * 32 * IDD, KIL + kbase + (size_t)wave * 32 * IDD);
;     for (int t = wave; t < ntile; t += NWAVES) {
;         const IdxKey k = kn;
;         if (t + NWAVES < ntile) idx_load_keyb(kn, KIH + kbase + (size_t)(t + NWAVES) * 32 * IDD, KIL + kbase + (size_t)(t + NWAVES) * 32 * IDD);
.LBB0_1212:
	s_add_i32 s0, s4, s12
	s_ashr_i32 s1, s0, 31
	s_lshl_b64 s[0:1], s[0:1], 9
	v_readlane_b32 s3, v238, 3
	s_add_u32 s0, s3, s0
	v_readlane_b32 s3, v238, 4
	s_addc_u32 s1, s3, s1
	v_mov_b32_e32 v3, v68
	v_lshlrev_b32_e32 v4, 3, v84
	global_store_dwordx2 v4, v[2:3], s[0:1]
	v_mov_b32_e32 v2, v0
	s_barrier
	s_nop 0
	v_readfirstlane_b32 s0, v2
	s_ashr_i32 s0, s0, 6
	s_cmp_ge_i32 s0, s11
	v_and_b32_e32 v84, 63, v2
	s_cbranch_scc1 .LBB0_1217
	v_and_b32_e32 v3, 31, v2
	v_lshrrev_b32_e32 v5, 5, v84
	v_lshrrev_b32_e32 v4, 1, v84
	v_and_b32_e32 v6, 2, v4
	v_bfe_u32 v7, v2, 4, 1
	v_and_b32_e32 v8, 3, v2
	v_and_or_b32 v8, v4, 4, v8
	v_or3_b32 v9, s10, v7, v6
	v_lshlrev_b32_e32 v10, 10, v9
	v_lshl_add_u32 v10, v8, 7, v10
	v_lshl_add_u32 v10, v5, 4, v10
	v_add_u32_e32 v11, 0x1000, v10
	s_lshl_b32 s1, s10, 5
	v_lshl_add_u32 v12, v5, 6, s1
	s_add_u32 s6, s34, 0x22e82000
	s_addc_u32 s7, s35, 0
	s_lshl_b32 s1, s0, 12
	v_lshl_add_u32 v94, v3, 7, s1
	v_lshl_add_u32 v94, v5, 4, v94
	s_sub_i32 s3, s11, s0
	s_add_i32 s3, s3, 7
	s_lshr_b32 s3, s3, 3
	global_load_dwordx4 v[102:105], v94, s[6:7]
	global_load_dwordx4 v[106:109], v94, s[6:7] offset:32
	global_load_dwordx4 v[110:113], v94, s[6:7] offset:64
	global_load_dwordx4 v[114:117], v94, s[6:7] offset:96
	s_cmp_lt_u32 s3, 2
	s_cbranch_scc1 .LidxB_pd
	v_add_u32_e32 v95, 0x8000, v94
	global_load_dwordx4 v[118:121], v95, s[6:7]
	global_load_dwordx4 v[122:125], v95, s[6:7] offset:32
	global_load_dwordx4 v[126:129], v95, s[6:7] offset:64
	global_load_dwordx4 v[130:133], v95, s[6:7] offset:96
	s_cmp_lt_u32 s3, 3
	s_cbranch_scc1 .LidxB_pd
	v_add_u32_e32 v95, 0x10000, v94
	global_load_dwordx4 v[134:137], v95, s[6:7]
	global_load_dwordx4 v[138:141], v95, s[6:7] offset:32
	global_load_dwordx4 v[142:145], v95, s[6:7] offset:64
	global_load_dwordx4 v[146:149], v95, s[6:7] offset:96
	s_cmp_lt_u32 s3, 4
	s_cbranch_scc1 .LidxB_pd
	v_add_u32_e32 v95, 0x18000, v94
	global_load_dwordx4 v[160:163], v95, s[6:7]
	global_load_dwordx4 v[164:167], v95, s[6:7] offset:32
	global_load_dwordx4 v[168:171], v95, s[6:7] offset:64
	global_load_dwordx4 v[172:175], v95, s[6:7] offset:96

; __device__ __forceinline__ void idx_load_q(IdxQ& q, const bf16_t* QI, const float* WI, int grow0, int lane) {
;     static_assert(IDX_SPLIT == 1, "q_idx is stored in bf16");
;     const int rho = lane & 31, kh = lane >> 5, ql = 2 * ((rho >> 2) & 1) + (rho >> 4), head = 4 * ((rho >> 3) & 1) + (rho & 3);
;     const bf16_t* src = QI + (size_t)(grow0 + ql) * 512 + head * IDD + kh * 8;
; #pragma unroll
;     for (int ks = 0; ks < 4; ++ks) { q.hi[ks] = *(const bf16x8*)(src + ks * 16); q.lo[ks] = q.hi[ks]; }
; #pragma unroll
;     for (int e = 0; e < 2; ++e) {
;         const float* wsrc = WI + (size_t)(grow0 + 2 * kh + e) * 8;
;         const f32x4 a = *(const f32x4*)wsrc, b = *(const f32x4*)(wsrc + 4);
; #pragma unroll
;         for (int i = 0; i < 4; ++i) { q.w[e * 8 + i] = a[i] * IDX_W_SCALE; q.w[e * 8 + 4 + i] = b[i] * IDX_W_SCALE; }
;     }
.LidxB_gp:
	v_mov_b64_e32 v[18:19], v[176:177]
	v_mov_b64_e32 v[20:21], v[178:179]
	v_mov_b64_e32 v[22:23], v[180:181]
	v_mov_b64_e32 v[24:25], v[182:183]
	v_mov_b64_e32 v[26:27], v[184:185]
	v_mov_b64_e32 v[28:29], v[186:187]
	v_mov_b64_e32 v[30:31], v[188:189]
	v_mov_b64_e32 v[32:33], v[190:191]
	v_mov_b64_e32 v[34:35], v[192:193]
	v_mov_b64_e32 v[36:37], v[194:195]
	v_mov_b64_e32 v[38:39], v[196:197]
	v_mov_b64_e32 v[40:41], v[198:199]
	v_mov_b64_e32 v[42:43], v[200:201]
	v_mov_b64_e32 v[44:45], v[202:203]
	v_mov_b64_e32 v[46:47], v[204:205]
	v_mov_b64_e32 v[48:49], v[206:207]
	v_mov_b64_e32 v[50:51], v[208:209]
	v_mov_b64_e32 v[52:53], v[210:211]
	v_mov_b64_e32 v[54:55], v[212:213]
	v_mov_b64_e32 v[56:57], v[214:215]
	v_mov_b64_e32 v[58:59], v[216:217]
	v_mov_b64_e32 v[60:61], v[218:219]
	v_mov_b64_e32 v[62:63], v[220:221]
	v_mov_b64_e32 v[64:65], v[222:223]
	v_mov_b64_e32 v[66:67], v[224:225]
	v_mov_b64_e32 v[68:69], v[226:227]
	v_mov_b64_e32 v[70:71], v[228:229]
	v_mov_b64_e32 v[72:73], v[230:231]
	v_mov_b64_e32 v[74:75], v[232:233]
	v_mov_b64_e32 v[76:77], v[234:235]
	v_mov_b64_e32 v[78:79], v[240:241]
	v_mov_b64_e32 v[80:81], v[242:243]
	v_mul_f32_e32 v50, 0x3eb504f3, v50
	v_mul_f32_e32 v51, 0x3eb504f3, v51
	v_mul_f32_e32 v52, 0x3eb504f3, v52
	v_mul_f32_e32 v53, 0x3eb504f3, v53
	v_mul_f32_e32 v54, 0x3eb504f3, v54
	v_mul_f32_e32 v55, 0x3eb504f3, v55
	v_mul_f32_e32 v56, 0x3eb504f3, v56
	v_mul_f32_e32 v57, 0x3eb504f3, v57
	v_mul_f32_e32 v58, 0x3eb504f3, v58
	v_mul_f32_e32 v59, 0x3eb504f3, v59
	v_mul_f32_e32 v60, 0x3eb504f3, v60
	v_mul_f32_e32 v61, 0x3eb504f3, v61
	v_mul_f32_e32 v62, 0x3eb504f3, v62
	v_mul_f32_e32 v63, 0x3eb504f3, v63
	v_mul_f32_e32 v64, 0x3eb504f3, v64
	v_mul_f32_e32 v65, 0x3eb504f3, v65
	v_mul_f32_e32 v66, 0x3eb504f3, v66
	v_mul_f32_e32 v67, 0x3eb504f3, v67
	v_mul_f32_e32 v68, 0x3eb504f3, v68
	v_mul_f32_e32 v69, 0x3eb504f3, v69
	v_mul_f32_e32 v70, 0x3eb504f3, v70
	v_mul_f32_e32 v71, 0x3eb504f3, v71
	v_mul_f32_e32 v72, 0x3eb504f3, v72
	v_mul_f32_e32 v73, 0x3eb504f3, v73
	v_mul_f32_e32 v74, 0x3eb504f3, v74
	v_mul_f32_e32 v75, 0x3eb504f3, v75
	v_mul_f32_e32 v76, 0x3eb504f3, v76
	v_mul_f32_e32 v77, 0x3eb504f3, v77
	v_mul_f32_e32 v78, 0x3eb504f3, v78
	v_mul_f32_e32 v79, 0x3eb504f3, v79
	v_mul_f32_e32 v80, 0x3eb504f3, v80
	v_mul_f32_e32 v81, 0x3eb504f3, v81
	s_branch .LidxB_go_0
